# DSA softmax batched x4 only
# baseline (speedup 1.0000x reference)
.LBB0_270:
	s_waitcnt vmcnt(0)
	v_and_b32_e32 v98, 64, v198
	v_xor_b32_e32 v2, 16, v198
	v_add_u32_e32 v14, 64, v98
	v_cmp_lt_i32_e32 vcc, v2, v14
	v_max_f32_e32 v3, v204, v204
	v_mov_b32_e32 v15, 0
	v_cndmask_b32_e32 v2, v198, v2, vcc
	v_lshlrev_b32_e32 v99, 2, v2
	ds_bpermute_b32 v2, v99, v204
	s_waitcnt lgkmcnt(0)
	v_max_f32_e32 v2, v2, v2
	v_max_f32_e32 v2, v3, v2
	v_xor_b32_e32 v3, 32, v198
	v_cmp_lt_i32_e32 vcc, v3, v14
	s_nop 1
	v_cndmask_b32_e32 v3, v198, v3, vcc
	v_lshlrev_b32_e32 v100, 2, v3
	ds_bpermute_b32 v3, v100, v2
	v_cmp_ge_u32_e32 vcc, s50, v182
	s_waitcnt lgkmcnt(0)
	v_max_f32_e32 v3, v3, v3
	v_max_f32_e32 v2, v2, v3
	v_or_b32_e32 v3, v98, v181
	v_lshlrev_b32_e32 v3, 2, v3
	ds_bpermute_b32 v2, v3, v2
	v_mov_b32_e32 v15, 0
	v_mov_b32_e32 v4, v182
	s_movk_i32 s42, 8
	s_waitcnt lgkmcnt(0)
	v_mov_b32_e32 v3, v203
.Ldsa_sm_loop:
	ds_read_b32 v5, v3
	ds_read_b32 v6, v3 offset:256
	ds_read_b32 v7, v3 offset:512
	ds_read_b32 v8, v3 offset:768
	s_waitcnt lgkmcnt(0)
	v_sub_f32_e32 v5, v5, v2
	v_sub_f32_e32 v6, v6, v2
	v_sub_f32_e32 v7, v7, v2
	v_sub_f32_e32 v8, v8, v2
	v_mul_f32_e32 v5, 0x3fb8aa3b, v5
	v_mul_f32_e32 v6, 0x3fb8aa3b, v6
	v_mul_f32_e32 v7, 0x3fb8aa3b, v7
	v_mul_f32_e32 v8, 0x3fb8aa3b, v8
	v_exp_f32_e32 v5, v5
	v_exp_f32_e32 v6, v6
	v_exp_f32_e32 v7, v7
	v_exp_f32_e32 v8, v8
	v_add_u32_e32 v9, 8, v4
	v_add_u32_e32 v10, 16, v4
	v_add_u32_e32 v11, 24, v4
	ds_write_b32 v3, v5
	ds_write_b32 v3, v6 offset:256
	ds_write_b32 v3, v7 offset:512
	ds_write_b32 v3, v8 offset:768
	v_cmp_ge_u32_e32 vcc, s50, v4
	s_nop 1
	v_cndmask_b32_e32 v12, 0, v5, vcc
	v_add_f32_e32 v15, v15, v12
	v_cmp_ge_u32_e32 vcc, s50, v9
	s_nop 1
	v_cndmask_b32_e32 v12, 0, v6, vcc
	v_add_f32_e32 v15, v15, v12
	v_cmp_ge_u32_e32 vcc, s50, v10
	s_nop 1
	v_cndmask_b32_e32 v12, 0, v7, vcc
	v_add_f32_e32 v15, v15, v12
	v_cmp_ge_u32_e32 vcc, s50, v11
	s_nop 1
	v_cndmask_b32_e32 v12, 0, v8, vcc
	v_add_f32_e32 v15, v15, v12
	v_add_u32_e32 v4, 32, v4
	v_add_u32_e32 v3, 0x400, v3
	s_sub_u32 s42, s42, 1
	s_cmp_lg_u32 s42, 0
	s_cbranch_scc1 .Ldsa_sm_loop
.LBB0_274:
	s_waitcnt lgkmcnt(0)
	v_min_i32_e32 v2, s50, v183
	v_lshl_add_u32 v2, v2, 1, s51
	v_min_i32_e32 v3, s50, v184
	v_min_i32_e32 v4, s50, v185
	v_min_i32_e32 v5, s50, v186
	v_min_i32_e32 v6, s50, v187
	v_min_i32_e32 v7, s50, v188
	v_min_i32_e32 v8, s50, v189
	v_min_i32_e32 v9, s50, v176
	v_lshl_add_u32 v3, v3, 1, s51
	v_lshl_add_u32 v4, v4, 1, s51
	v_lshl_add_u32 v5, v5, 1, s51
	v_lshl_add_u32 v6, v6, 1, s51
	v_lshl_add_u32 v7, v7, 1, s51
	v_lshl_add_u32 v8, v8, 1, s51
	v_lshl_add_u32 v9, v9, 1, s51
	ds_read_u16 v2, v2
	ds_read_u16 v10, v3
	ds_read_u16 v11, v4
	ds_read_u16 v12, v5
	ds_read_u16 v18, v6
	ds_read_u16 v19, v7
	ds_read_u16 v20, v8
	ds_read_u16 v21, v9
	s_waitcnt lgkmcnt(7)
	v_lshlrev_b32_e32 v150, 9, v2
	v_lshl_add_u64 v[2:3], v[162:163], 0, v[150:151]
	s_waitcnt lgkmcnt(6)
	v_lshlrev_b32_e32 v150, 9, v10
	v_lshl_add_u64 v[6:7], v[162:163], 0, v[150:151]
	s_waitcnt lgkmcnt(5)
	v_lshlrev_b32_e32 v150, 9, v11
	v_lshl_add_u64 v[10:11], v[162:163], 0, v[150:151]
	s_waitcnt lgkmcnt(4)
	v_lshlrev_b32_e32 v150, 9, v12
	v_lshl_add_u64 v[16:17], v[162:163], 0, v[150:151]
	s_waitcnt lgkmcnt(3)
	v_lshlrev_b32_e32 v150, 9, v18
	global_load_dwordx4 v[2:5], v[2:3], off offset:256
	s_nop 0
	global_load_dwordx4 v[6:9], v[6:7], off offset:256
	s_nop 0
	global_load_dwordx4 v[10:13], v[10:11], off offset:256
	s_nop 0
	global_load_dwordx4 v[46:49], v[16:17], off offset:256
	v_lshl_add_u64 v[16:17], v[162:163], 0, v[150:151]
	s_waitcnt lgkmcnt(2)
	v_lshlrev_b32_e32 v150, 9, v19
	v_lshl_add_u64 v[18:19], v[162:163], 0, v[150:151]
	s_waitcnt lgkmcnt(1)
	v_lshlrev_b32_e32 v150, 9, v20
	global_load_dwordx4 v[50:53], v[16:17], off offset:256
	global_load_dwordx4 v[54:57], v[18:19], off offset:256
	v_lshl_add_u64 v[16:17], v[162:163], 0, v[150:151]
	s_waitcnt lgkmcnt(0)
	v_lshlrev_b32_e32 v150, 9, v21
	v_lshl_add_u64 v[18:19], v[162:163], 0, v[150:151]
	global_load_dwordx4 v[58:61], v[16:17], off offset:256
	global_load_dwordx4 v[62:65], v[18:19], off offset:256
	v_xor_b32_e32 v16, 8, v198
	v_cmp_lt_i32_e32 vcc, v16, v14
	s_add_i32 s34, s50, 4
	v_mov_b32_e32 v92, 0
	v_cndmask_b32_e32 v14, v198, v16, vcc
	v_lshlrev_b32_e32 v14, 2, v14
	ds_bpermute_b32 v14, v14, v15
	s_mov_b32 s76, 8
	s_lshr_b32 s77, s34, 2
	v_mov_b32_e32 v103, v176
	v_mov_b32_e32 v93, v92
	s_waitcnt lgkmcnt(0)
	v_add_f32_e32 v101, v15, v14
	ds_bpermute_b32 v102, v99, v101
	v_mov_b32_e32 v88, v92
	v_mov_b32_e32 v89, v92
	v_mov_b32_e32 v80, v92
	v_mov_b32_e32 v81, v92
	v_mov_b32_e32 v72, v92
	v_mov_b32_e32 v73, v92
	v_mov_b32_e32 v96, v92
	v_mov_b32_e32 v97, v92
	v_mov_b32_e32 v86, v92
	v_mov_b32_e32 v87, v92
	v_mov_b32_e32 v78, v92
	v_mov_b32_e32 v79, v92
	v_mov_b32_e32 v70, v92
	v_mov_b32_e32 v71, v92
	v_mov_b32_e32 v94, v92
	v_mov_b32_e32 v95, v92
	v_mov_b32_e32 v84, v92
	v_mov_b32_e32 v85, v92
	v_mov_b32_e32 v74, v92
	v_mov_b32_e32 v75, v92
	v_mov_b32_e32 v68, v92
	v_mov_b32_e32 v69, v92
	v_mov_b32_e32 v90, v92
	v_mov_b32_e32 v91, v92
	v_mov_b32_e32 v82, v92
	v_mov_b32_e32 v83, v92
	v_mov_b32_e32 v76, v92
	v_mov_b32_e32 v77, v92
	v_mov_b32_e32 v66, v92
	v_mov_b32_e32 v67, v92
	s_branch .LBB0_276
